# p3_tile V^T LDS transpose: XOR swizzle removes 4-way bank conflict on ds_read_u16
# baseline (speedup 1.0000x reference)
.LBB0_486:
	v_mul_lo_u32 v0, v28, s18
	v_add_u32_e32 v5, 0, v0
	v_ashrrev_i32_e32 v0, 2, v27
	v_ashrrev_i32_e32 v1, 31, v0
	v_lshlrev_b64 v[2:3], 14, v[0:1]
	v_lshlrev_b32_e32 v1, 1, v27
	v_and_b32_e32 v6, 6, v1
	v_lshl_add_u64 v[2:3], s[4:5], 0, v[2:3]
	s_ashr_i32 s61, s60, 31
	v_lshl_add_u32 v8, v0, 1, 0
	v_lshlrev_b32_e32 v10, 4, v6
	v_xor_b32_e32 v8, v8, v10
	v_lshl_or_b32 v0, v6, 3, 8
	v_lshlrev_b32_e32 v24, 5, v29
	v_lshl_add_u64 v[2:3], s[60:61], 1, v[2:3]
	v_mul_u32_u24_e32 v9, 0x110, v0
	v_mad_u32_u24 v4, v6, s19, v8
	v_lshlrev_b32_e32 v6, 4, v6
	v_mov_b32_e32 v7, v25
	v_mov_b32_e32 v27, v26
	v_lshl_add_u64 v[0:1], v[38:39], 0, v[24:25]
	v_lshl_add_u64 v[2:3], v[2:3], 0, v[6:7]
	s_mov_b32 s9, 0
	s_mov_b64 s[58:59], -1
	v_bfe_u32 v10, v28, 4, 2
	v_xor_b32_e32 v10, v29, v10
	v_lshl_add_u32 v5, v10, 5, v5
	v_add_u32_e32 v6, v8, v9
